# attention: second-half QK MFMAs interleaved with first-half softmax VALU
# baseline (speedup 1.0000x reference)
; __device__ __forceinline__ unsigned cvt_pk_bf16(float lo, float hi) { unsigned r; asm("v_cvt_pk_bf16_f32 %0, %1, %2" : "=v"(r) : "v"(lo), "v"(hi)); return r; }
; __device__ __forceinline__ void attn_unit(int b, int qb, int kvh, const bf16_t* __restrict__ QP, const bf16_t* __restrict__ KP, const bf16_t* __restrict__ VT, const float* sink, bf16_t* MIX, unsigned char* ldsb, int tid, int wave, int lane) {
;     ...
;         f32x4 s[4][2];
; #pragma unroll
;         for (int kt = 0; kt < 4; ++kt)
; #pragma unroll
;             for (int qt = 0; qt < 2; ++qt) { f32x4 a = (f32x4){0.f, 0.f, 0.f, 0.f};
; #pragma unroll
;                 for (int ks = 0; ks < 2; ++ks) a = __builtin_amdgcn_mfma_f32_16x16x32_bf16(kf[kt][ks], qf[qt][ks], a, 0, 0, 0);
;                 s[kt][qt] = a; }
;         bf16x8 pf[2][2];
; #pragma unroll
;         for (int qt = 0; qt < 2; ++qt) { const int qpos = q0 + qt * 16 + fr; float mx = -3.0e38f;
; #pragma unroll
;             for (int kt = 0; kt < 4; ++kt)
; #pragma unroll
;                 for (int j = 0; j < 4; ++j) { float v = s[kt][qt][j]; if (needmask) { const int dd = ks0 + kt * 16 + 4 * fq + j - qpos; if (dd > 128 || dd < -128) v = -1.0e30f; s[kt][qt][j] = v; } mx = fmaxf(mx, v); }
;             mx = fmaxf(mx, __shfl_xor(mx, 16)); mx = fmaxf(mx, __shfl_xor(mx, 32));
;             const float mnew = fmaxf(mrun[qt], mx), alpha = __builtin_amdgcn_exp2f(mrun[qt] - mnew); mrun[qt] = mnew; float ls = 0.f;
; #pragma unroll
;             for (int kt = 0; kt < 4; ++kt)
; #pragma unroll
;                 for (int j = 0; j < 4; ++j) { const float p = __builtin_amdgcn_exp2f(s[kt][qt][j] - mnew); s[kt][qt][j] = p; ls += p; }
;             lrun[qt] = lrun[qt] * alpha + ls;
; #pragma unroll
;             for (int dt = 0; dt < 4; ++dt) o[dt][qt] *= alpha;
; #pragma unroll
;             for (int kk = 0; kk < 2; ++kk) { u32x4 w; w.x = cvt_pk_bf16(s[2 * kk][qt][0], s[2 * kk][qt][1]); w.y = cvt_pk_bf16(s[2 * kk][qt][2], s[2 * kk][qt][3]);
;                 w.z = cvt_pk_bf16(s[2 * kk + 1][qt][0], s[2 * kk + 1][qt][1]); w.w = cvt_pk_bf16(s[2 * kk + 1][qt][2], s[2 * kk + 1][qt][3]); pf[qt][kk] = __builtin_bit_cast(bf16x8, w); } }
.Lat_qk_plain:
	s_waitcnt lgkmcnt(7)
	v_mfma_f32_16x16x32_bf16 v[80:83], v[112:115], v[16:19], v[196:199]
	v_mfma_f32_16x16x32_bf16 v[80:83], v[116:119], v[20:23], v[80:83]
	v_mfma_f32_16x16x32_bf16 v[84:87], v[112:115], v[24:27], v[196:199]
	v_mfma_f32_16x16x32_bf16 v[84:87], v[116:119], v[28:31], v[84:87]
	v_mfma_f32_16x16x32_bf16 v[88:91], v[120:123], v[16:19], v[196:199]
	v_mfma_f32_16x16x32_bf16 v[88:91], v[124:127], v[20:23], v[88:91]
	v_mfma_f32_16x16x32_bf16 v[92:95], v[120:123], v[24:27], v[196:199]
	v_mfma_f32_16x16x32_bf16 v[92:95], v[124:127], v[28:31], v[92:95]
	ds_read_b64 v[170:171], v11 offset:14336
	ds_read_b64 v[148:149], v12 offset:8192
	ds_read_b64 v[150:151], v13 offset:8192
	ds_read_b64 v[156:157], v12 offset:10240
	ds_read_b64 v[158:159], v13 offset:10240
	ds_read_b64 v[164:165], v12 offset:12288
	ds_read_b64 v[166:167], v13 offset:12288
	ds_read_b64 v[172:173], v12 offset:14336
	ds_read_b64 v[174:175], v13 offset:14336
	v_mfma_f32_16x16x32_bf16 v[96:99], v[128:131], v[16:19], v[196:199]
	v_mfma_f32_16x16x32_bf16 v[96:99], v[132:135], v[20:23], v[96:99]
	v_exp_f32_e32 v80, v80
	v_exp_f32_e32 v81, v81
	v_exp_f32_e32 v82, v82
	v_exp_f32_e32 v83, v83
	v_pk_add_f32 v[192:193], v[192:193], v[80:81]
	v_pk_add_f32 v[192:193], v[192:193], v[82:83]
	v_cvt_pk_bf16_f32 v176, v80, v81
	v_cvt_pk_bf16_f32 v177, v82, v83
	v_mfma_f32_16x16x32_bf16 v[100:103], v[128:131], v[24:27], v[196:199]
	v_mfma_f32_16x16x32_bf16 v[100:103], v[132:135], v[28:31], v[100:103]
	v_exp_f32_e32 v84, v84
	v_exp_f32_e32 v85, v85
	v_exp_f32_e32 v86, v86
	v_exp_f32_e32 v87, v87
	v_pk_add_f32 v[194:195], v[194:195], v[84:85]
	v_pk_add_f32 v[194:195], v[194:195], v[86:87]
	v_cvt_pk_bf16_f32 v184, v84, v85
	v_cvt_pk_bf16_f32 v185, v86, v87
	v_mfma_f32_16x16x32_bf16 v[104:107], v[136:139], v[16:19], v[196:199]
	v_mfma_f32_16x16x32_bf16 v[104:107], v[140:143], v[20:23], v[104:107]
	v_exp_f32_e32 v88, v88
	v_exp_f32_e32 v89, v89
	v_exp_f32_e32 v90, v90
	v_exp_f32_e32 v91, v91
	v_pk_add_f32 v[192:193], v[192:193], v[88:89]
	v_pk_add_f32 v[192:193], v[192:193], v[90:91]
	v_cvt_pk_bf16_f32 v178, v88, v89
	v_cvt_pk_bf16_f32 v179, v90, v91
	v_mfma_f32_16x16x32_bf16 v[108:111], v[136:139], v[24:27], v[196:199]
	v_mfma_f32_16x16x32_bf16 v[108:111], v[140:143], v[28:31], v[108:111]
	v_exp_f32_e32 v92, v92
	v_exp_f32_e32 v93, v93
	v_exp_f32_e32 v94, v94
	v_exp_f32_e32 v95, v95
	v_pk_add_f32 v[194:195], v[194:195], v[92:93]
	v_pk_add_f32 v[194:195], v[194:195], v[94:95]
	v_cvt_pk_bf16_f32 v186, v92, v93
	v_cvt_pk_bf16_f32 v187, v94, v95
	s_branch .Lat_qk_done
.Lat_qk_A:
	s_waitcnt lgkmcnt(7)
	v_mfma_f32_16x16x32_bf16 v[80:83], v[112:115], v[16:19], v[212:215]
	v_mfma_f32_16x16x32_bf16 v[80:83], v[116:119], v[20:23], v[80:83]
	v_mfma_f32_16x16x32_bf16 v[84:87], v[112:115], v[24:27], v[208:211]
	v_mfma_f32_16x16x32_bf16 v[84:87], v[116:119], v[28:31], v[84:87]
	v_mfma_f32_16x16x32_bf16 v[88:91], v[120:123], v[16:19], v[216:219]
	v_mfma_f32_16x16x32_bf16 v[88:91], v[124:127], v[20:23], v[88:91]
	v_mfma_f32_16x16x32_bf16 v[92:95], v[120:123], v[24:27], v[212:215]
	v_mfma_f32_16x16x32_bf16 v[92:95], v[124:127], v[28:31], v[92:95]
	ds_read_b64 v[170:171], v11 offset:14336
	ds_read_b64 v[148:149], v12 offset:8192
	ds_read_b64 v[150:151], v13 offset:8192
	ds_read_b64 v[156:157], v12 offset:10240
	ds_read_b64 v[158:159], v13 offset:10240
	ds_read_b64 v[164:165], v12 offset:12288
	ds_read_b64 v[166:167], v13 offset:12288
	ds_read_b64 v[172:173], v12 offset:14336
	ds_read_b64 v[174:175], v13 offset:14336
	v_mfma_f32_16x16x32_bf16 v[96:99], v[128:131], v[16:19], v[220:223]
	v_mfma_f32_16x16x32_bf16 v[96:99], v[132:135], v[20:23], v[96:99]
	v_exp_f32_e32 v80, v80
	v_exp_f32_e32 v81, v81
	v_exp_f32_e32 v82, v82
	v_exp_f32_e32 v83, v83
	v_pk_add_f32 v[192:193], v[192:193], v[80:81]
	v_pk_add_f32 v[192:193], v[192:193], v[82:83]
	v_cvt_pk_bf16_f32 v176, v80, v81
	v_cvt_pk_bf16_f32 v177, v82, v83
	v_mfma_f32_16x16x32_bf16 v[100:103], v[128:131], v[24:27], v[216:219]
	v_mfma_f32_16x16x32_bf16 v[100:103], v[132:135], v[28:31], v[100:103]
	v_exp_f32_e32 v84, v84
	v_exp_f32_e32 v85, v85
	v_exp_f32_e32 v86, v86
	v_exp_f32_e32 v87, v87
	v_pk_add_f32 v[194:195], v[194:195], v[84:85]
	v_pk_add_f32 v[194:195], v[194:195], v[86:87]
	v_cvt_pk_bf16_f32 v184, v84, v85
	v_cvt_pk_bf16_f32 v185, v86, v87
	v_mfma_f32_16x16x32_bf16 v[104:107], v[136:139], v[16:19], v[224:227]
	v_mfma_f32_16x16x32_bf16 v[104:107], v[140:143], v[20:23], v[104:107]
	v_exp_f32_e32 v88, v88
	v_exp_f32_e32 v89, v89
	v_exp_f32_e32 v90, v90
	v_exp_f32_e32 v91, v91
	v_pk_add_f32 v[192:193], v[192:193], v[88:89]
	v_pk_add_f32 v[192:193], v[192:193], v[90:91]
	v_cvt_pk_bf16_f32 v178, v88, v89
	v_cvt_pk_bf16_f32 v179, v90, v91
	v_mfma_f32_16x16x32_bf16 v[108:111], v[136:139], v[24:27], v[220:223]
	v_mfma_f32_16x16x32_bf16 v[108:111], v[140:143], v[28:31], v[108:111]
	v_exp_f32_e32 v92, v92
	v_exp_f32_e32 v93, v93
	v_exp_f32_e32 v94, v94
	v_exp_f32_e32 v95, v95
	v_pk_add_f32 v[194:195], v[194:195], v[92:93]
	v_pk_add_f32 v[194:195], v[194:195], v[94:95]
	v_cvt_pk_bf16_f32 v186, v92, v93
	v_cvt_pk_bf16_f32 v187, v94, v95
	s_branch .Lat_qk_done
; __device__ __forceinline__ unsigned cvt_pk_bf16(float lo, float hi) { unsigned r; asm("v_cvt_pk_bf16_f32 %0, %1, %2" : "=v"(r) : "v"(lo), "v"(hi)); return r; }
; __device__ __forceinline__ void attn_unit(int b, int qb, int kvh, const bf16_t* __restrict__ QP, const bf16_t* __restrict__ KP, const bf16_t* __restrict__ VT, const float* sink, bf16_t* MIX, unsigned char* ldsb, int tid, int wave, int lane) {
;     ...
;         f32x4 s[4][2];
; #pragma unroll
;         for (int kt = 0; kt < 4; ++kt)
; #pragma unroll
;             for (int qt = 0; qt < 2; ++qt) { f32x4 a = (f32x4){0.f, 0.f, 0.f, 0.f};
; #pragma unroll
;                 for (int ks = 0; ks < 2; ++ks) a = __builtin_amdgcn_mfma_f32_16x16x32_bf16(kf[kt][ks], qf[qt][ks], a, 0, 0, 0);
;                 s[kt][qt] = a; }
;         bf16x8 pf[2][2];
; #pragma unroll
;         for (int qt = 0; qt < 2; ++qt) { const int qpos = q0 + qt * 16 + fr; float mx = -3.0e38f;
; #pragma unroll
;             for (int kt = 0; kt < 4; ++kt)
; #pragma unroll
;                 for (int j = 0; j < 4; ++j) { float v = s[kt][qt][j]; if (needmask) { const int dd = ks0 + kt * 16 + 4 * fq + j - qpos; if (dd > 128 || dd < -128) v = -1.0e30f; s[kt][qt][j] = v; } mx = fmaxf(mx, v); }
;             mx = fmaxf(mx, __shfl_xor(mx, 16)); mx = fmaxf(mx, __shfl_xor(mx, 32));
;             const float mnew = fmaxf(mrun[qt], mx), alpha = __builtin_amdgcn_exp2f(mrun[qt] - mnew); mrun[qt] = mnew; float ls = 0.f;
; #pragma unroll
;             for (int kt = 0; kt < 4; ++kt)
; #pragma unroll
;                 for (int j = 0; j < 4; ++j) { const float p = __builtin_amdgcn_exp2f(s[kt][qt][j] - mnew); s[kt][qt][j] = p; ls += p; }
;             lrun[qt] = lrun[qt] * alpha + ls;
; #pragma unroll
;             for (int dt = 0; dt < 4; ++dt) o[dt][qt] *= alpha;
; #pragma unroll
;             for (int kk = 0; kk < 2; ++kk) { u32x4 w; w.x = cvt_pk_bf16(s[2 * kk][qt][0], s[2 * kk][qt][1]); w.y = cvt_pk_bf16(s[2 * kk][qt][2], s[2 * kk][qt][3]);
;                 w.z = cvt_pk_bf16(s[2 * kk + 1][qt][0], s[2 * kk + 1][qt][1]); w.w = cvt_pk_bf16(s[2 * kk + 1][qt][2], s[2 * kk + 1][qt][3]); pf[qt][kk] = __builtin_bit_cast(bf16x8, w); } }
.Lat_qk_B:
	s_waitcnt lgkmcnt(7)
	v_mfma_f32_16x16x32_bf16 v[80:83], v[112:115], v[16:19], v[232:235]
	v_mfma_f32_16x16x32_bf16 v[80:83], v[116:119], v[20:23], v[80:83]
	v_mfma_f32_16x16x32_bf16 v[84:87], v[112:115], v[24:27], v[228:231]
	v_mfma_f32_16x16x32_bf16 v[84:87], v[116:119], v[28:31], v[84:87]
	v_mfma_f32_16x16x32_bf16 v[88:91], v[120:123], v[16:19], v[236:239]
	v_mfma_f32_16x16x32_bf16 v[88:91], v[124:127], v[20:23], v[88:91]
	v_mfma_f32_16x16x32_bf16 v[92:95], v[120:123], v[24:27], v[232:235]
	v_mfma_f32_16x16x32_bf16 v[92:95], v[124:127], v[28:31], v[92:95]
	ds_read_b64 v[170:171], v11 offset:14336
	ds_read_b64 v[148:149], v12 offset:8192
	ds_read_b64 v[150:151], v13 offset:8192
	ds_read_b64 v[156:157], v12 offset:10240
	ds_read_b64 v[158:159], v13 offset:10240
	ds_read_b64 v[164:165], v12 offset:12288
	ds_read_b64 v[166:167], v13 offset:12288
	ds_read_b64 v[172:173], v12 offset:14336
	ds_read_b64 v[174:175], v13 offset:14336
	v_mfma_f32_16x16x32_bf16 v[96:99], v[128:131], v[16:19], v[240:243]
	v_mfma_f32_16x16x32_bf16 v[96:99], v[132:135], v[20:23], v[96:99]
	v_exp_f32_e32 v80, v80
	v_exp_f32_e32 v81, v81
	v_exp_f32_e32 v82, v82
	v_exp_f32_e32 v83, v83
	v_pk_add_f32 v[192:193], v[192:193], v[80:81]
	v_pk_add_f32 v[192:193], v[192:193], v[82:83]
	v_cvt_pk_bf16_f32 v176, v80, v81
	v_cvt_pk_bf16_f32 v177, v82, v83
	v_mfma_f32_16x16x32_bf16 v[100:103], v[128:131], v[24:27], v[236:239]
	v_mfma_f32_16x16x32_bf16 v[100:103], v[132:135], v[28:31], v[100:103]
	v_exp_f32_e32 v84, v84
	v_exp_f32_e32 v85, v85
	v_exp_f32_e32 v86, v86
	v_exp_f32_e32 v87, v87
	v_pk_add_f32 v[194:195], v[194:195], v[84:85]
	v_pk_add_f32 v[194:195], v[194:195], v[86:87]
	v_cvt_pk_bf16_f32 v184, v84, v85
	v_cvt_pk_bf16_f32 v185, v86, v87
	v_mfma_f32_16x16x32_bf16 v[104:107], v[136:139], v[16:19], v[244:247]
	v_mfma_f32_16x16x32_bf16 v[104:107], v[140:143], v[20:23], v[104:107]
	v_exp_f32_e32 v88, v88
	v_exp_f32_e32 v89, v89
	v_exp_f32_e32 v90, v90
	v_exp_f32_e32 v91, v91
	v_pk_add_f32 v[192:193], v[192:193], v[88:89]
	v_pk_add_f32 v[192:193], v[192:193], v[90:91]
	v_cvt_pk_bf16_f32 v178, v88, v89
	v_cvt_pk_bf16_f32 v179, v90, v91
	v_mfma_f32_16x16x32_bf16 v[108:111], v[136:139], v[24:27], v[240:243]
	v_mfma_f32_16x16x32_bf16 v[108:111], v[140:143], v[28:31], v[108:111]
	v_exp_f32_e32 v92, v92
	v_exp_f32_e32 v93, v93
	v_exp_f32_e32 v94, v94
	v_exp_f32_e32 v95, v95
	v_pk_add_f32 v[194:195], v[194:195], v[92:93]
	v_pk_add_f32 v[194:195], v[194:195], v[94:95]
	v_cvt_pk_bf16_f32 v186, v92, v93
	v_cvt_pk_bf16_f32 v187, v94, v95
; __device__ __forceinline__ unsigned cvt_pk_bf16(float lo, float hi) { unsigned r; asm("v_cvt_pk_bf16_f32 %0, %1, %2" : "=v"(r) : "v"(lo), "v"(hi)); return r; }
; __device__ __forceinline__ void attn_unit(int b, int qb, int kvh, const bf16_t* __restrict__ QP, const bf16_t* __restrict__ KP, const bf16_t* __restrict__ VT, const float* sink, bf16_t* MIX, unsigned char* ldsb, int tid, int wave, int lane) {
;     ...
;                 for (int j = 0; j < 4; ++j) { const float p = __builtin_amdgcn_exp2f(s[kt][qt][j] - mnew); s[kt][qt][j] = p; ls += p; }
;             lrun[qt] = lrun[qt] * alpha + ls;
; #pragma unroll
;             for (int dt = 0; dt < 4; ++dt) o[dt][qt] *= alpha;
; #pragma unroll
;             for (int kk = 0; kk < 2; ++kk) { u32x4 w; w.x = cvt_pk_bf16(s[2 * kk][qt][0], s[2 * kk][qt][1]); w.y = cvt_pk_bf16(s[2 * kk][qt][2], s[2 * kk][qt][3]);
;                 w.z = cvt_pk_bf16(s[2 * kk + 1][qt][0], s[2 * kk + 1][qt][1]); w.w = cvt_pk_bf16(s[2 * kk + 1][qt][2], s[2 * kk + 1][qt][3]); pf[qt][kk] = __builtin_bit_cast(bf16x8, w); } }
; #pragma unroll
;         for (int dt = 0; dt < 4; ++dt)
; #pragma unroll
;             for (int kk = 0; kk < 2; ++kk) { u32x4 w; w.x = vr[dt][kk][0].x; w.y = vr[dt][kk][0].y; w.z = vr[dt][kk][1].x; w.w = vr[dt][kk][1].y; const bf16x8 vf = __builtin_bit_cast(bf16x8, w);
; #pragma unroll
;                 for (int qt = 0; qt < 2; ++qt) o[dt][qt] = __builtin_amdgcn_mfma_f32_16x16x32_bf16(vf, pf[qt][kk], o[dt][qt], 0, 0, 0); }
;         if (jt + 1 < nT) { bf16_t* Kn = lb + ((jt + 1) & 1) * 9216; *(u32x4*)(Kn + lr * 72 + lc * 8) = kreg; *(u32x4*)(Kn + 4608 + lr * 72 + lc * 8) = vreg; }
;         __syncthreads();
;     }
;     ...
; #pragma unroll
;     for (int qt = 0; qt < 2; ++qt) { float l = lrun[qt]; l += __shfl_xor(l, 16); l += __shfl_xor(l, 32); const float inv = 1.0f / l;
;         bf16_t* op = MIX + (size_t)(b * 4096 + q0 + qt * 16 + fr) * 1024 + hq * 64 + 4 * fq;
; #pragma unroll
;         for (int dt = 0; dt < 4; ++dt) { const f32x4 a = o[dt][qt] * inv; u32x2 w; w.x = cvt_pk_bf16(a[0], a[1]); w.y = cvt_pk_bf16(a[2], a[3]); *(u32x2*)(op + dt * 16) = w; } }
.Lat_qk_done:
	s_waitcnt lgkmcnt(8)
	v_exp_f32_e32 v96, v96
	v_exp_f32_e32 v97, v97
	v_exp_f32_e32 v98, v98
	v_exp_f32_e32 v99, v99
	v_pk_add_f32 v[192:193], v[192:193], v[96:97]
	v_pk_add_f32 v[192:193], v[192:193], v[98:99]
	v_cvt_pk_bf16_f32 v180, v96, v97
	v_cvt_pk_bf16_f32 v181, v98, v99
	v_mfma_f32_16x16x32_bf16 v[48:51], v[144:147], v[176:179], v[48:51]
	v_mfma_f32_16x16x32_bf16 v[52:55], v[144:147], v[184:187], v[52:55]
	v_exp_f32_e32 v100, v100
	v_exp_f32_e32 v101, v101
	v_exp_f32_e32 v102, v102
	v_exp_f32_e32 v103, v103
	v_pk_add_f32 v[194:195], v[194:195], v[100:101]
	v_pk_add_f32 v[194:195], v[194:195], v[102:103]
	v_cvt_pk_bf16_f32 v188, v100, v101
	v_cvt_pk_bf16_f32 v189, v102, v103
	v_mfma_f32_16x16x32_bf16 v[56:59], v[152:155], v[176:179], v[56:59]
	v_mfma_f32_16x16x32_bf16 v[60:63], v[152:155], v[184:187], v[60:63]
	v_exp_f32_e32 v104, v104
	v_exp_f32_e32 v105, v105
	v_exp_f32_e32 v106, v106
	v_exp_f32_e32 v107, v107
	v_pk_add_f32 v[192:193], v[192:193], v[104:105]
	v_pk_add_f32 v[192:193], v[192:193], v[106:107]
	v_cvt_pk_bf16_f32 v182, v104, v105
	v_cvt_pk_bf16_f32 v183, v106, v107
	v_mfma_f32_16x16x32_bf16 v[64:67], v[160:163], v[176:179], v[64:67]
	v_mfma_f32_16x16x32_bf16 v[68:71], v[160:163], v[184:187], v[68:71]
	v_exp_f32_e32 v108, v108
	v_exp_f32_e32 v109, v109
	v_exp_f32_e32 v110, v110
	v_exp_f32_e32 v111, v111
	v_pk_add_f32 v[194:195], v[194:195], v[108:109]
	v_pk_add_f32 v[194:195], v[194:195], v[110:111]
	v_cvt_pk_bf16_f32 v190, v108, v109
	v_cvt_pk_bf16_f32 v191, v110, v111
	v_mfma_f32_16x16x32_bf16 v[72:75], v[168:171], v[176:179], v[72:75]
	v_mfma_f32_16x16x32_bf16 v[76:79], v[168:171], v[184:187], v[76:79]
	s_waitcnt lgkmcnt(0)
	v_mfma_f32_16x16x32_bf16 v[48:51], v[148:151], v[180:183], v[48:51]
	v_mfma_f32_16x16x32_bf16 v[52:55], v[148:151], v[188:191], v[52:55]
	v_mfma_f32_16x16x32_bf16 v[56:59], v[156:159], v[180:183], v[56:59]
	v_mfma_f32_16x16x32_bf16 v[60:63], v[156:159], v[188:191], v[60:63]
	v_mfma_f32_16x16x32_bf16 v[64:67], v[164:167], v[180:183], v[64:67]
	v_mfma_f32_16x16x32_bf16 v[68:71], v[164:167], v[188:191], v[68:71]
	v_mfma_f32_16x16x32_bf16 v[72:75], v[172:175], v[180:183], v[72:75]
	v_mfma_f32_16x16x32_bf16 v[76:79], v[172:175], v[188:191], v[76:79]
	s_add_u32 s27, s27, 1
	s_add_u32 s30, s30, 1
	s_cmp_lt_u32 s30, s25
	s_cbranch_scc1 .Lat_cont
	s_lshl_b32 s0, s31, 24
	s_add_u32 s38, s52, s0
	s_addc_u32 s39, s53, 0
	s_nop 7
	v_add_f32_e32 v202, v192, v193
	v_add_f32_e32 v204, v194, v195
	v_mov_b32_e32 v203, v202
	v_mov_b32_e32 v205, v204
	s_nop 1
	v_permlane16_swap_b32_e32 v202, v203
	v_permlane16_swap_b32_e32 v204, v205
	s_nop 0
	v_add_f32_e32 v202, v202, v203
	v_add_f32_e32 v204, v204, v205
	v_mov_b32_e32 v203, v202
	v_mov_b32_e32 v205, v204
	s_nop 1
	v_permlane32_swap_b32_e32 v202, v203
	v_permlane32_swap_b32_e32 v204, v205
	s_nop 0
	v_add_f32_e32 v202, v202, v203
	v_add_f32_e32 v204, v204, v205
	v_rcp_f32_e32 v202, v202
	v_rcp_f32_e32 v204, v204
	s_nop 0
	v_pk_mul_f32 v[48:49], v[48:49], v[202:203] op_sel_hi:[1,0]
	v_pk_mul_f32 v[50:51], v[50:51], v[202:203] op_sel_hi:[1,0]
	v_cvt_pk_bf16_f32 v80, v48, v49
	v_cvt_pk_bf16_f32 v81, v50, v51
	global_store_dwordx2 v200, v[80:81], s[38:39]
	v_pk_mul_f32 v[52:53], v[52:53], v[204:205] op_sel_hi:[1,0]
	v_pk_mul_f32 v[54:55], v[54:55], v[204:205] op_sel_hi:[1,0]
	v_cvt_pk_bf16_f32 v82, v52, v53
	v_cvt_pk_bf16_f32 v83, v54, v55
	global_store_dwordx2 v201, v[82:83], s[38:39]
	v_pk_mul_f32 v[56:57], v[56:57], v[202:203] op_sel_hi:[1,0]
	v_pk_mul_f32 v[58:59], v[58:59], v[202:203] op_sel_hi:[1,0]
	v_cvt_pk_bf16_f32 v84, v56, v57
	v_cvt_pk_bf16_f32 v85, v58, v59
	global_store_dwordx2 v200, v[84:85], s[38:39] offset:32
	v_pk_mul_f32 v[60:61], v[60:61], v[204:205] op_sel_hi:[1,0]
	v_pk_mul_f32 v[62:63], v[62:63], v[204:205] op_sel_hi:[1,0]
	v_cvt_pk_bf16_f32 v86, v60, v61
	v_cvt_pk_bf16_f32 v87, v62, v63
	global_store_dwordx2 v201, v[86:87], s[38:39] offset:32
	v_pk_mul_f32 v[64:65], v[64:65], v[202:203] op_sel_hi:[1,0]
	v_pk_mul_f32 v[66:67], v[66:67], v[202:203] op_sel_hi:[1,0]
	v_cvt_pk_bf16_f32 v88, v64, v65
	v_cvt_pk_bf16_f32 v89, v66, v67
	global_store_dwordx2 v200, v[88:89], s[38:39] offset:64
	v_pk_mul_f32 v[68:69], v[68:69], v[204:205] op_sel_hi:[1,0]
	v_pk_mul_f32 v[70:71], v[70:71], v[204:205] op_sel_hi:[1,0]
	v_cvt_pk_bf16_f32 v90, v68, v69
	v_cvt_pk_bf16_f32 v91, v70, v71
	global_store_dwordx2 v201, v[90:91], s[38:39] offset:64
	v_pk_mul_f32 v[72:73], v[72:73], v[202:203] op_sel_hi:[1,0]
	v_pk_mul_f32 v[74:75], v[74:75], v[202:203] op_sel_hi:[1,0]
	v_cvt_pk_bf16_f32 v92, v72, v73
	v_cvt_pk_bf16_f32 v93, v74, v75
	global_store_dwordx2 v200, v[92:93], s[38:39] offset:96
	v_pk_mul_f32 v[76:77], v[76:77], v[204:205] op_sel_hi:[1,0]
	v_pk_mul_f32 v[78:79], v[78:79], v[204:205] op_sel_hi:[1,0]
	v_cvt_pk_bf16_f32 v94, v76, v77
	v_cvt_pk_bf16_f32 v95, v78, v79
	global_store_dwordx2 v201, v[94:95], s[38:39] offset:96
	v_mov_b32_e32 v16, v32
	v_mov_b32_e32 v17, v33
	v_mov_b32_e32 v18, v34
	v_mov_b32_e32 v19, v35
	v_mov_b32_e32 v20, v36
	v_mov_b32_e32 v21, v37
	v_mov_b32_e32 v22, v38
	v_mov_b32_e32 v23, v39
	v_mov_b32_e32 v24, v40
	v_mov_b32_e32 v25, v41
	v_mov_b32_e32 v26, v42
	v_mov_b32_e32 v27, v43
	v_mov_b32_e32 v28, v44
	v_mov_b32_e32 v29, v45
	v_mov_b32_e32 v30, v46
	v_mov_b32_e32 v31, v47
	s_mov_b32 s30, 0
	s_add_u32 s31, s31, 1
